# GEMM merged phases + P5 micro-edits: select cmp_e64/addc, permlane swaps instead of ds_bpermute, attention LDS reads batched with fewer waits, bfe+and masks, Q wait ladder removed
# speedup vs baseline: 1.0108x; 1.0023x over previous
; __device__ __forceinline__ void phase_attn(const Params& P, unsigned char* lds) {
;     ...
;             unsigned prefix = 0u;
;     ...
;                 const unsigned cand = prefix | (1u << bit); const int c31 = (int)(cand >> 1);
;                 int lt0 = 0, lt1 = 0;
; #pragma unroll
;                 for (int ch = 0; ch < 9; ++ch) {
;                     if (ch < nch) {
; #pragma unroll
;                         for (int jj = 0; jj < 8; jj += 2) { lt0 += (int)((unsigned)((int)(key[ch * 8 + jj] >> 1) - c31) >> 31); lt1 += (int)((unsigned)((int)(key[ch * 8 + jj + 1] >> 1) - c31) >> 31); }
;                     }
;                 }
;                 int cnt = nch * 8 - (lt0 + lt1);
;                 cnt += __builtin_amdgcn_update_dpp(0, cnt, 0xB1, 0xF, 0xF, true);
;                 cnt += __builtin_amdgcn_update_dpp(0, cnt, 0x4E, 0xF, 0xF, true);
;                 cnt += __builtin_amdgcn_update_dpp(0, cnt, 0x141, 0xF, 0xF, true);
;                 cnt += __builtin_amdgcn_update_dpp(0, cnt, 0x140, 0xF, 0xF, true);
;                 cnt += __shfl_xor(cnt, 16);
;                 if (cnt >= 256) prefix = cand;
.LBB0_654:
	v_add_u32_e32 v246, v247, v246
	v_sub_u32_e32 v246, s79, v246
	s_movk_i32 s0, 0xff
	s_cmp_lt_u32 s30, 9
	v_add_u32_dpp v246, v246, v246 quad_perm:[1,0,3,2] row_mask:0xf bank_mask:0xf bound_ctrl:1
	s_nop 1
	v_add_u32_dpp v246, v246, v246 quad_perm:[2,3,0,1] row_mask:0xf bank_mask:0xf bound_ctrl:1
	s_nop 1
	v_add_u32_dpp v246, v246, v246 row_half_mirror row_mask:0xf bank_mask:0xf bound_ctrl:1
	s_nop 1
	v_add_u32_dpp v246, v246, v246 row_mirror row_mask:0xf bank_mask:0xf bound_ctrl:1
	v_mov_b32_e32 v247, v246
	s_nop 1
	v_permlane16_swap_b32_e32 v246, v247
	v_add_u32_e32 v246, v246, v247
	v_cmp_lt_i32_e32 vcc, s0, v246
	s_nop 1
	v_cndmask_b32_e32 v243, v243, v245, vcc
	s_cbranch_scc1 .LBB0_671
.LBB0_655:
	s_add_i32 s30, s30, -1
	s_lshl_b32 s0, 1, s30
	v_or_b32_e32 v245, s0, v243
	v_lshrrev_b32_e32 v248, 1, v245
	v_cmp_lt_u32_e64 s[48:49], v132, v248
	v_cmp_lt_u32_e64 s[88:89], v138, v248
	v_cmp_lt_u32_e64 s[92:93], v131, v248
	v_cmp_lt_u32_e64 s[94:95], v133, v248
	v_addc_co_u32_e64 v246, s[96:97], 0, 0, s[48:49]
	v_addc_co_u32_e64 v247, s[96:97], 0, 0, s[88:89]
	v_addc_co_u32_e64 v246, s[96:97], 0, v246, s[92:93]
	v_addc_co_u32_e64 v247, s[96:97], 0, v247, s[94:95]
	v_cmp_lt_u32_e64 s[48:49], v134, v248
	v_cmp_lt_u32_e64 s[88:89], v136, v248
	v_cmp_lt_u32_e64 s[92:93], v135, v248
	v_cmp_lt_u32_e64 s[94:95], v137, v248
	v_addc_co_u32_e64 v246, s[96:97], 0, v246, s[48:49]
	v_addc_co_u32_e64 v247, s[96:97], 0, v247, s[88:89]
	v_addc_co_u32_e64 v246, s[96:97], 0, v246, s[92:93]
	v_addc_co_u32_e64 v247, s[96:97], 0, v247, s[94:95]
	s_and_b64 vcc, exec, s[20:21]
	s_cbranch_vccz .LBB0_663
	s_and_b64 vcc, exec, s[18:19]
	s_cbranch_vccz .LBB0_664

; __device__ __forceinline__ void phase_attn(const Params& P, unsigned char* lds) {
;     ...
;                 int lt0 = 0, lt1 = 0;
; #pragma unroll
;                 for (int ch = 0; ch < 9; ++ch) {
;                     if (ch < nch) {
; #pragma unroll
;                         for (int jj = 0; jj < 8; jj += 2) { lt0 += (int)((unsigned)((int)(key[ch * 8 + jj] >> 1) - c31) >> 31); lt1 += (int)((unsigned)((int)(key[ch * 8 + jj + 1] >> 1) - c31) >> 31); }
;                     }
;                 }
.LBB0_663:
	v_cmp_lt_u32_e64 s[48:49], v139, v248
	v_cmp_lt_u32_e64 s[88:89], v140, v248
	v_cmp_lt_u32_e64 s[92:93], v143, v248
	v_cmp_lt_u32_e64 s[94:95], v144, v248
	v_addc_co_u32_e64 v246, s[96:97], 0, v246, s[48:49]
	v_addc_co_u32_e64 v247, s[96:97], 0, v247, s[88:89]
	v_addc_co_u32_e64 v246, s[96:97], 0, v246, s[92:93]
	v_addc_co_u32_e64 v247, s[96:97], 0, v247, s[94:95]
	v_cmp_lt_u32_e64 s[48:49], v141, v248
	v_cmp_lt_u32_e64 s[88:89], v145, v248
	v_cmp_lt_u32_e64 s[92:93], v142, v248
	v_cmp_lt_u32_e64 s[94:95], v146, v248
	v_addc_co_u32_e64 v246, s[96:97], 0, v246, s[48:49]
	v_addc_co_u32_e64 v247, s[96:97], 0, v247, s[88:89]
	v_addc_co_u32_e64 v246, s[96:97], 0, v246, s[92:93]
	v_addc_co_u32_e64 v247, s[96:97], 0, v247, s[94:95]
	s_and_b64 vcc, exec, s[18:19]
	s_cbranch_vccnz .LBB0_657
.LBB0_664:
	v_cmp_lt_u32_e64 s[48:49], v147, v248
	v_cmp_lt_u32_e64 s[88:89], v148, v248
	v_cmp_lt_u32_e64 s[92:93], v151, v248
	v_cmp_lt_u32_e64 s[94:95], v152, v248
	v_addc_co_u32_e64 v246, s[96:97], 0, v246, s[48:49]
	v_addc_co_u32_e64 v247, s[96:97], 0, v247, s[88:89]
	v_addc_co_u32_e64 v246, s[96:97], 0, v246, s[92:93]
	v_addc_co_u32_e64 v247, s[96:97], 0, v247, s[94:95]
	v_cmp_lt_u32_e64 s[48:49], v149, v248
	v_cmp_lt_u32_e64 s[88:89], v153, v248
	v_cmp_lt_u32_e64 s[92:93], v150, v248
	v_cmp_lt_u32_e64 s[94:95], v154, v248
	v_addc_co_u32_e64 v246, s[96:97], 0, v246, s[48:49]
	v_addc_co_u32_e64 v247, s[96:97], 0, v247, s[88:89]
	v_addc_co_u32_e64 v246, s[96:97], 0, v246, s[92:93]
	v_addc_co_u32_e64 v247, s[96:97], 0, v247, s[94:95]
	s_and_b64 vcc, exec, s[16:17]
	s_cbranch_vccnz .LBB0_658
.LBB0_665:
	v_cmp_lt_u32_e64 s[48:49], v155, v248
	v_cmp_lt_u32_e64 s[88:89], v156, v248
	v_cmp_lt_u32_e64 s[92:93], v159, v248
	v_cmp_lt_u32_e64 s[94:95], v160, v248
	v_addc_co_u32_e64 v246, s[96:97], 0, v246, s[48:49]
	v_addc_co_u32_e64 v247, s[96:97], 0, v247, s[88:89]
	v_addc_co_u32_e64 v246, s[96:97], 0, v246, s[92:93]
	v_addc_co_u32_e64 v247, s[96:97], 0, v247, s[94:95]
	v_cmp_lt_u32_e64 s[48:49], v157, v248
	v_cmp_lt_u32_e64 s[88:89], v161, v248
	v_cmp_lt_u32_e64 s[92:93], v158, v248
	v_cmp_lt_u32_e64 s[94:95], v184, v248
	v_addc_co_u32_e64 v246, s[96:97], 0, v246, s[48:49]
	v_addc_co_u32_e64 v247, s[96:97], 0, v247, s[88:89]
	v_addc_co_u32_e64 v246, s[96:97], 0, v246, s[92:93]
	v_addc_co_u32_e64 v247, s[96:97], 0, v247, s[94:95]
	s_and_b64 vcc, exec, s[14:15]
	s_cbranch_vccnz .LBB0_659
.LBB0_666:
	v_cmp_lt_u32_e64 s[48:49], v185, v248
	v_cmp_lt_u32_e64 s[88:89], v186, v248
	v_cmp_lt_u32_e64 s[92:93], v189, v248
	v_cmp_lt_u32_e64 s[94:95], v190, v248
	v_addc_co_u32_e64 v246, s[96:97], 0, v246, s[48:49]
	v_addc_co_u32_e64 v247, s[96:97], 0, v247, s[88:89]
	v_addc_co_u32_e64 v246, s[96:97], 0, v246, s[92:93]
	v_addc_co_u32_e64 v247, s[96:97], 0, v247, s[94:95]
	v_cmp_lt_u32_e64 s[48:49], v187, v248
	v_cmp_lt_u32_e64 s[88:89], v191, v248
	v_cmp_lt_u32_e64 s[92:93], v188, v248
	v_cmp_lt_u32_e64 s[94:95], v192, v248
	v_addc_co_u32_e64 v246, s[96:97], 0, v246, s[48:49]
	v_addc_co_u32_e64 v247, s[96:97], 0, v247, s[88:89]
	v_addc_co_u32_e64 v246, s[96:97], 0, v246, s[92:93]
	v_addc_co_u32_e64 v247, s[96:97], 0, v247, s[94:95]
	s_and_b64 vcc, exec, s[12:13]
	s_cbranch_vccnz .LBB0_660
.LBB0_667:
	v_cmp_lt_u32_e64 s[48:49], v193, v248
	v_cmp_lt_u32_e64 s[88:89], v194, v248
	v_cmp_lt_u32_e64 s[92:93], v197, v248
	v_cmp_lt_u32_e64 s[94:95], v198, v248
	v_addc_co_u32_e64 v246, s[96:97], 0, v246, s[48:49]
	v_addc_co_u32_e64 v247, s[96:97], 0, v247, s[88:89]
	v_addc_co_u32_e64 v246, s[96:97], 0, v246, s[92:93]
	v_addc_co_u32_e64 v247, s[96:97], 0, v247, s[94:95]
	v_cmp_lt_u32_e64 s[48:49], v195, v248
	v_cmp_lt_u32_e64 s[88:89], v199, v248
	v_cmp_lt_u32_e64 s[92:93], v196, v248
	v_cmp_lt_u32_e64 s[94:95], v226, v248
	v_addc_co_u32_e64 v246, s[96:97], 0, v246, s[48:49]
	v_addc_co_u32_e64 v247, s[96:97], 0, v247, s[88:89]
	v_addc_co_u32_e64 v246, s[96:97], 0, v246, s[92:93]
	v_addc_co_u32_e64 v247, s[96:97], 0, v247, s[94:95]
	s_and_b64 vcc, exec, s[10:11]
	s_cbranch_vccnz .LBB0_661
.LBB0_668:
	v_cmp_lt_u32_e64 s[48:49], v227, v248
	v_cmp_lt_u32_e64 s[88:89], v228, v248
	v_cmp_lt_u32_e64 s[92:93], v231, v248
	v_cmp_lt_u32_e64 s[94:95], v232, v248
	v_addc_co_u32_e64 v246, s[96:97], 0, v246, s[48:49]
	v_addc_co_u32_e64 v247, s[96:97], 0, v247, s[88:89]
	v_addc_co_u32_e64 v246, s[96:97], 0, v246, s[92:93]
	v_addc_co_u32_e64 v247, s[96:97], 0, v247, s[94:95]
	v_cmp_lt_u32_e64 s[48:49], v229, v248
	v_cmp_lt_u32_e64 s[88:89], v233, v248
	v_cmp_lt_u32_e64 s[92:93], v230, v248
	v_cmp_lt_u32_e64 s[94:95], v234, v248
	v_addc_co_u32_e64 v246, s[96:97], 0, v246, s[48:49]
	v_addc_co_u32_e64 v247, s[96:97], 0, v247, s[88:89]
	v_addc_co_u32_e64 v246, s[96:97], 0, v246, s[92:93]
	v_addc_co_u32_e64 v247, s[96:97], 0, v247, s[94:95]
	s_and_b64 vcc, exec, s[8:9]
	s_cbranch_vccnz .LBB0_662
.LBB0_669:
	v_cmp_lt_u32_e64 s[48:49], v235, v248
	v_cmp_lt_u32_e64 s[88:89], v236, v248
	v_cmp_lt_u32_e64 s[92:93], v239, v248
	v_cmp_lt_u32_e64 s[94:95], v240, v248
	v_addc_co_u32_e64 v246, s[96:97], 0, v246, s[48:49]
	v_addc_co_u32_e64 v247, s[96:97], 0, v247, s[88:89]
	v_addc_co_u32_e64 v246, s[96:97], 0, v246, s[92:93]
	v_addc_co_u32_e64 v247, s[96:97], 0, v247, s[94:95]
	v_cmp_lt_u32_e64 s[48:49], v237, v248
	v_cmp_lt_u32_e64 s[88:89], v241, v248
	v_cmp_lt_u32_e64 s[92:93], v238, v248
	v_cmp_lt_u32_e64 s[94:95], v242, v248
	v_addc_co_u32_e64 v246, s[96:97], 0, v246, s[48:49]
	v_addc_co_u32_e64 v247, s[96:97], 0, v247, s[88:89]
	v_addc_co_u32_e64 v246, s[96:97], 0, v246, s[92:93]
	v_addc_co_u32_e64 v247, s[96:97], 0, v247, s[94:95]
	s_and_b64 vcc, exec, s[6:7]
	s_cbranch_vccnz .LBB0_654

; #define ATT_STORE(SK, SV, buf_) do { _Pragma("unroll") for (int i_ = 0; i_ < 2; ++i_) { const int key_ = kkey0 + 16 * i_; \
;                 *(u32x4*)(lds + ATT_K_OFF + (buf_) * 16384 + key_ * 512 + (kch >> 4) * 256 + (((kch & 15) ^ (key_ & 15)) * 16)) = SK[i_]; \
;                 *(u32x4*)(lds + ATT_V_OFF + (buf_) * 20480 + (vrow0 + 128 * i_) * 80 + vc4 * 16) = SV[i_]; } } while (0)
; __device__ __forceinline__ void phase_attn(const Params& P, unsigned char* lds) {
;     ...
;             bf16x8 Qf[8];
;             { const bf16_t* qp = Z1 + (size_t)(b * SEQ + s0 + lr) * LDZ + wave * 128 + hh * 8;
; #pragma unroll
;               for (int kk = 0; kk < 8; ++kk) Qf[kk] = *(const bf16x8*)(qp + kk * 16); }
; #pragma unroll
;             for (int kk = 0; kk < 8; ++kk) asm volatile("" :: "v"(Qf[kk]));
;             f32x16 o[4];
; #pragma unroll
;             for (int d = 0; d < 4; ++d)
; #pragma unroll
;                 for (int i = 0; i < 16; ++i) o[d][i] = 0.f;
;             float m = -1e30f, l = 0.f;
;             const int kkey0 = tid >> 5, kch = tid & 31;
;             const int vrow0 = tid >> 2, vc4 = tid & 3;
;             u32x4 sKa[2], sVa[2], sKb[2], sVb[2];
;     ...
;             ATT_LOAD(sKa, sVa, 0); ATT_STORE(sKa, sVa, 0);
;             if (1 < ntiles) ATT_LOAD(sKb, sVb, 1);
;             __syncthreads();
.LBB0_816:
	s_add_i32 s75, s75, s73
	v_or_b32_e32 v160, s75, v163
	v_mad_u64_u32 v[2:3], s[0:1], v160, s34, v[170:171]
	s_waitcnt lgkmcnt(0)
	s_barrier
	global_load_dwordx4 v[96:99], v[2:3], off
	global_load_dwordx4 v[100:103], v[2:3], off offset:32
	global_load_dwordx4 v[104:107], v[2:3], off offset:64
	global_load_dwordx4 v[108:111], v[2:3], off offset:96
	global_load_dwordx4 v[112:115], v[2:3], off offset:128
	global_load_dwordx4 v[116:119], v[2:3], off offset:160
	global_load_dwordx4 v[120:123], v[2:3], off offset:192
	global_load_dwordx4 v[124:127], v[2:3], off offset:224
	s_mulk_i32 s74, 0x4100
	v_or_b32_e32 v0, s74, v202
	v_or_b32_e32 v3, s73, v169
	v_lshlrev_b32_e32 v0, 6, v0
	v_or_b32_e32 v10, s73, v206
	v_lshl_add_u64 v[4:5], v[172:173], 0, v[0:1]
	v_mul_u32_u24_e32 v0, 0x1600, v3
	s_add_i32 s10, s73, -16
	v_lshl_add_u64 v[6:7], v[178:179], 0, v[0:1]
	v_mul_u32_u24_e32 v0, 0x1600, v10
	v_mov_b32_e32 v183, v1
	v_add_u32_e32 v2, s10, v169
	v_add_co_u32_e32 v8, vcc, s22, v4
	v_lshl_add_u64 v[10:11], s[44:45], 0, v[0:1]
	s_mov_b32 s0, 0x16000
	v_cndmask_b32_e64 v2, v2, v209, s[4:5]
	v_addc_co_u32_e32 v9, vcc, 0, v5, vcc
	v_lshl_add_u64 v[10:11], v[10:11], 0, v[182:183]
	v_mul_i32_i24_e32 v2, 0x1600, v2
	v_add_lshl_u32 v0, v207, s74, 6
	v_add_co_u32_e32 v14, vcc, s0, v10
	v_ashrrev_i32_e32 v3, 31, v2
	v_lshl_add_u64 v[12:13], v[172:173], 0, v[0:1]
	v_addc_co_u32_e32 v15, vcc, 0, v11, vcc
	v_lshl_add_u64 v[2:3], v[178:179], 0, v[2:3]
	v_add_co_u32_e32 v16, vcc, s22, v12
	s_and_b32 s0, s70, 7
	s_nop 0
	v_addc_co_u32_e32 v17, vcc, 0, v13, vcc
	v_mov_b32_e32 v0, v1
	v_mov_b32_e32 v161, v1
	v_mov_b32_e32 v188, 0xf149f2ca
	v_mov_b32_e32 v183, 0
	s_mov_b32 s11, 3
	v_mov_b32_e32 v186, v212
	v_mov_b32_e32 v187, v211
	v_mad_u64_u32 v[184:185], s[0:1], s0, v214, v[180:181]
	global_load_dwordx4 v[128:131], v[2:3], off offset:2048
	global_load_dwordx4 v[136:139], v[4:5], off
	global_load_dwordx4 v[144:147], v[6:7], off offset:2048
	global_load_dwordx4 v[152:155], v[8:9], off
	global_load_dwordx4 v[132:135], v[10:11], off offset:2048
	global_load_dwordx4 v[140:143], v[12:13], off
	global_load_dwordx4 v[148:151], v[14:15], off offset:2048
	global_load_dwordx4 v[156:159], v[16:17], off
	v_mov_b32_e32 v14, v1
	v_mov_b32_e32 v15, v1
	v_mov_b32_e32 v2, v1
	v_mov_b32_e32 v3, v1
	v_mov_b32_e32 v4, v1
	v_mov_b32_e32 v5, v1
	v_mov_b32_e32 v6, v1
	v_mov_b32_e32 v7, v1
	v_mov_b32_e32 v8, v1
	v_mov_b32_e32 v9, v1
	v_mov_b32_e32 v10, v1
	v_mov_b32_e32 v11, v1
	v_mov_b32_e32 v12, v1
	v_mov_b32_e32 v13, v1
	v_mov_b64_e32 v[30:31], v[14:15]
	v_mov_b64_e32 v[46:47], v[14:15]
	v_mov_b64_e32 v[62:63], v[14:15]
	v_mov_b64_e32 v[78:79], v[14:15]
	v_mov_b64_e32 v[28:29], v[12:13]
	v_mov_b64_e32 v[26:27], v[10:11]
	v_mov_b64_e32 v[24:25], v[8:9]
	v_mov_b64_e32 v[22:23], v[6:7]
	v_mov_b64_e32 v[20:21], v[4:5]
	v_mov_b64_e32 v[18:19], v[2:3]
	v_mov_b64_e32 v[16:17], v[0:1]
	v_mov_b64_e32 v[44:45], v[12:13]
	v_mov_b64_e32 v[42:43], v[10:11]
	v_mov_b64_e32 v[40:41], v[8:9]
	v_mov_b64_e32 v[38:39], v[6:7]
	v_mov_b64_e32 v[36:37], v[4:5]
	v_mov_b64_e32 v[34:35], v[2:3]
	v_mov_b64_e32 v[32:33], v[0:1]
	v_mov_b64_e32 v[60:61], v[12:13]
	v_mov_b64_e32 v[58:59], v[10:11]
	v_mov_b64_e32 v[56:57], v[8:9]
	v_mov_b64_e32 v[54:55], v[6:7]
	v_mov_b64_e32 v[52:53], v[4:5]
	v_mov_b64_e32 v[50:51], v[2:3]
	v_mov_b64_e32 v[48:49], v[0:1]
	v_mov_b64_e32 v[76:77], v[12:13]
	v_mov_b64_e32 v[74:75], v[10:11]
	v_mov_b64_e32 v[72:73], v[8:9]
	v_mov_b64_e32 v[70:71], v[6:7]
	v_mov_b64_e32 v[68:69], v[4:5]
	v_mov_b64_e32 v[66:67], v[2:3]
	v_mov_b64_e32 v[64:65], v[0:1]
	s_waitcnt vmcnt(7)
	ds_write_b128 v215, v[128:131]
	s_waitcnt vmcnt(6)
	ds_write_b128 v216, v[136:139] offset:32768
	s_waitcnt vmcnt(5)
	ds_write_b128 v215, v[144:147] offset:8192
	s_waitcnt vmcnt(4)
	ds_write_b128 v216, v[152:155] offset:43008
	s_waitcnt lgkmcnt(0)
	s_barrier
	s_branch .LBB0_818

; __device__ __forceinline__ void phase_attn(const Params& P, unsigned char* lds) {
;     ...
;             auto tile_body = [&](const int tile, const int buf) __attribute__((always_inline)) {
;                 f32x16 S;
; #pragma unroll
;                 for (int i = 0; i < 16; ++i) S[i] = 0.f;
;                 const unsigned char* kb = lds + ATT_K_OFF + buf * 16384 + lr * 512 + g * 256;
; #pragma unroll
;                 for (int kk = 0; kk < 8; ++kk) { const bf16x8 Kf = *(const bf16x8*)(kb + (((2 * kk + hh) ^ (lr & 15)) * 16)); S = __builtin_amdgcn_mfma_f32_32x32x16_bf16(Kf, Qf[kk], S, 0, 0, 0); }
;                 const unsigned bits2 = bm[lr * 65 + tile] >> (4 * hh);
;                 float mx = S[0];
; #pragma unroll
;                 for (int i = 1; i < 16; ++i) mx = __builtin_fmaxf(mx, S[i]);
;                 mx *= 0.12751743f;
;                 mx = __builtin_fmaxf(mx, __shfl_xor(mx, 32));
;                 if (__any(mx > m)) { const float mn = __builtin_fmaxf(m, mx), al = __builtin_amdgcn_exp2f(m - mn);
; #pragma unroll
;                     for (int d = 0; d < 4; ++d)
; #pragma unroll
;                         for (int i = 0; i < 16; ++i) o[d][i] *= al;
;                     l *= al; m = mn; }
;                 float pr[16];
; #pragma unroll
;                 for (int i = 0; i < 16; ++i) { const int mk = __builtin_amdgcn_sbfe((int)bits2, (i & 3) + 8 * (i >> 2), 1);
;                     const float e = __builtin_amdgcn_exp2f(__builtin_fmaf(S[i], 0.12751743f, -m));
;                     pr[i] = __int_as_float(__float_as_int(e) & mk); l += pr[i]; }
;                 bf16x8 Pf[2];
; #pragma unroll
;                 for (int s2 = 0; s2 < 2; ++s2) { u32x4 w; w.x = cvt_pk_bf16(pr[8 * s2 + 0], pr[8 * s2 + 1]); w.y = cvt_pk_bf16(pr[8 * s2 + 2], pr[8 * s2 + 3]);
;                     w.z = cvt_pk_bf16(pr[8 * s2 + 4], pr[8 * s2 + 5]); w.w = cvt_pk_bf16(pr[8 * s2 + 6], pr[8 * s2 + 7]); Pf[s2] = __builtin_bit_cast(bf16x8, w); }
;                 const unsigned char* vb = lds + ATT_V_OFF + buf * 20480 + (g * 128 + lr) * 80 + hh * 16;
; #pragma unroll
;                 for (int d = 0; d < 4; ++d)
; #pragma unroll
;                     for (int s2 = 0; s2 < 2; ++s2) { const bf16x8 Vf = *(const bf16x8*)(vb + d * 32 * 80 + s2 * 32); o[d] = __builtin_amdgcn_mfma_f32_32x32x16_bf16(Vf, Pf[s2], o[d], 0, 0, 0); }
;             };
.LBB0_820:
	ds_read_b128 v[2:5], v217
	ds_read_b128 v[6:9], v218
	ds_read_b128 v[226:229], v219
	ds_read_b128 v[230:233], v220
	ds_read_b128 v[234:237], v221
	ds_read_b128 v[238:241], v222
	ds_read_b128 v[242:245], v223
	ds_read_b128 v[246:249], v224
	s_waitcnt lgkmcnt(4)
	v_mfma_f32_32x32x16_bf16 v[80:95], v[2:5], v[96:99], 0
	v_mfma_f32_32x32x16_bf16 v[80:95], v[6:9], v[100:103], v[80:95]
	v_mfma_f32_32x32x16_bf16 v[80:95], v[226:229], v[104:107], v[80:95]
	v_mfma_f32_32x32x16_bf16 v[80:95], v[230:233], v[108:111], v[80:95]
	s_waitcnt lgkmcnt(0)
	v_mfma_f32_32x32x16_bf16 v[80:95], v[234:237], v[112:115], v[80:95]
	v_mfma_f32_32x32x16_bf16 v[80:95], v[238:241], v[116:119], v[80:95]
	v_mfma_f32_32x32x16_bf16 v[80:95], v[242:245], v[120:123], v[80:95]
	v_mfma_f32_32x32x16_bf16 v[80:95], v[246:249], v[124:127], v[80:95]
	ds_read_b128 v[190:193], v225 offset:32768
	ds_read_b128 v[194:197], v225 offset:32800
	ds_read_b128 v[226:229], v225 offset:35328
	ds_read_b128 v[230:233], v225 offset:35360
	ds_read_b128 v[234:237], v225 offset:37888
	ds_read_b128 v[238:241], v225 offset:37920
	ds_read_b128 v[242:245], v225 offset:40448
	ds_read_b128 v[246:249], v225 offset:40480
	s_nop 3
	v_max_f32_e32 v0, v81, v81
	v_max_f32_e32 v2, v80, v80
	v_max_f32_e32 v0, v2, v0
	v_max3_f32 v0, v0, v82, v83
	v_max3_f32 v0, v0, v84, v85
	v_max3_f32 v0, v0, v86, v87
	v_max3_f32 v0, v0, v88, v89
	v_max3_f32 v0, v0, v90, v91
	v_max3_f32 v0, v0, v92, v93
	v_max3_f32 v0, v0, v94, v95
	v_mul_f32_e32 v2, 0x3e0293ee, v0
	v_mov_b32_e32 v3, v2
	v_add_u32_e32 v0, -4, v187
	ds_read_b32 v0, v0
	v_permlane32_swap_b32_e32 v2, v3
	v_max_f32_e32 v2, v2, v3
	v_cmp_gt_f32_e32 vcc, v2, v188
	s_cbranch_vccz .LBB0_822
	v_max_f32_e32 v2, v2, v2
	v_max_f32_e32 v3, v188, v188
	v_max_f32_e32 v3, v3, v2
	v_sub_f32_e32 v2, v188, v3
	v_exp_f32_e32 v2, v2
	v_mov_b32_e32 v188, v3
	v_pk_mul_f32 v[78:79], v[78:79], v[2:3] op_sel_hi:[1,0]
	v_pk_mul_f32 v[76:77], v[76:77], v[2:3] op_sel_hi:[1,0]
	v_pk_mul_f32 v[74:75], v[74:75], v[2:3] op_sel_hi:[1,0]
	v_pk_mul_f32 v[72:73], v[72:73], v[2:3] op_sel_hi:[1,0]
	v_pk_mul_f32 v[70:71], v[70:71], v[2:3] op_sel_hi:[1,0]
	v_pk_mul_f32 v[68:69], v[68:69], v[2:3] op_sel_hi:[1,0]
	v_pk_mul_f32 v[66:67], v[66:67], v[2:3] op_sel_hi:[1,0]
	v_pk_mul_f32 v[64:65], v[64:65], v[2:3] op_sel_hi:[1,0]
	v_pk_mul_f32 v[62:63], v[62:63], v[2:3] op_sel_hi:[1,0]
	v_pk_mul_f32 v[60:61], v[60:61], v[2:3] op_sel_hi:[1,0]
	v_pk_mul_f32 v[58:59], v[58:59], v[2:3] op_sel_hi:[1,0]
	v_pk_mul_f32 v[56:57], v[56:57], v[2:3] op_sel_hi:[1,0]
	v_pk_mul_f32 v[54:55], v[54:55], v[2:3] op_sel_hi:[1,0]
	v_pk_mul_f32 v[52:53], v[52:53], v[2:3] op_sel_hi:[1,0]
	v_pk_mul_f32 v[50:51], v[50:51], v[2:3] op_sel_hi:[1,0]
	v_pk_mul_f32 v[48:49], v[48:49], v[2:3] op_sel_hi:[1,0]
	v_pk_mul_f32 v[46:47], v[46:47], v[2:3] op_sel_hi:[1,0]
	v_pk_mul_f32 v[44:45], v[44:45], v[2:3] op_sel_hi:[1,0]
	v_pk_mul_f32 v[42:43], v[42:43], v[2:3] op_sel_hi:[1,0]
	v_pk_mul_f32 v[40:41], v[40:41], v[2:3] op_sel_hi:[1,0]
	v_pk_mul_f32 v[38:39], v[38:39], v[2:3] op_sel_hi:[1,0]
	v_pk_mul_f32 v[36:37], v[36:37], v[2:3] op_sel_hi:[1,0]
	v_pk_mul_f32 v[34:35], v[34:35], v[2:3] op_sel_hi:[1,0]
	v_pk_mul_f32 v[32:33], v[32:33], v[2:3] op_sel_hi:[1,0]
	v_pk_mul_f32 v[30:31], v[30:31], v[2:3] op_sel_hi:[1,0]
	v_pk_mul_f32 v[28:29], v[28:29], v[2:3] op_sel_hi:[1,0]
	v_pk_mul_f32 v[26:27], v[26:27], v[2:3] op_sel_hi:[1,0]
	v_pk_mul_f32 v[24:25], v[24:25], v[2:3] op_sel_hi:[1,0]
	v_pk_mul_f32 v[22:23], v[22:23], v[2:3] op_sel_hi:[1,0]
	v_pk_mul_f32 v[20:21], v[20:21], v[2:3] op_sel_hi:[1,0]
	v_pk_mul_f32 v[18:19], v[18:19], v[2:3] op_sel_hi:[1,0]
	v_pk_mul_f32 v[16:17], v[16:17], v[2:3] op_sel_hi:[1,0]
	v_mul_f32_e32 v183, v183, v2
.LBB0_822:
	s_waitcnt lgkmcnt(0)
	v_lshrrev_b32_e32 v189, v208, v0
	v_fma_f32 v0, v80, s35, -v188
	v_exp_f32_e32 v0, v0
	v_fma_f32 v3, v81, s35, -v188
	v_exp_f32_e32 v3, v3
	v_bfe_i32 v250, v189, 0, 1
	v_bfe_i32 v251, v189, 1, 1
	v_fma_f32 v5, v83, s35, -v188
	v_and_b32_e32 v0, v0, v250
	v_exp_f32_e32 v5, v5
	v_bfe_i32 v252, v189, 2, 1
	v_and_b32_e32 v2, v3, v251
	v_fma_f32 v3, v82, s35, -v188
	v_exp_f32_e32 v3, v3
	v_bfe_i32 v198, v189, 3, 1
	v_fma_f32 v7, v85, s35, -v188
	v_and_b32_e32 v3, v3, v252
	v_exp_f32_e32 v7, v7
	v_bfe_i32 v250, v189, 8, 1
	v_and_b32_e32 v4, v5, v198
	v_fma_f32 v5, v84, s35, -v188
	v_exp_f32_e32 v5, v5
	v_bfe_i32 v251, v189, 9, 1
	v_fma_f32 v9, v87, s35, -v188
	v_and_b32_e32 v5, v5, v250
	v_exp_f32_e32 v9, v9
	v_bfe_i32 v252, v189, 10, 1
	v_and_b32_e32 v6, v7, v251
	v_fma_f32 v7, v86, s35, -v188
	v_exp_f32_e32 v7, v7
	v_bfe_i32 v198, v189, 11, 1
	v_fma_f32 v11, v89, s35, -v188
	v_and_b32_e32 v7, v7, v252
	v_exp_f32_e32 v11, v11
	v_bfe_i32 v250, v189, 16, 1
	v_and_b32_e32 v8, v9, v198
	v_fma_f32 v9, v88, s35, -v188
	v_exp_f32_e32 v9, v9
	v_bfe_i32 v251, v189, 17, 1
	v_fma_f32 v13, v91, s35, -v188
	v_and_b32_e32 v9, v9, v250
	v_exp_f32_e32 v13, v13
	v_bfe_i32 v252, v189, 18, 1
	v_and_b32_e32 v10, v11, v251
	v_fma_f32 v11, v90, s35, -v188
	v_exp_f32_e32 v11, v11
	v_bfe_i32 v198, v189, 19, 1
	v_fma_f32 v15, v93, s35, -v188
	v_and_b32_e32 v11, v11, v252
	v_exp_f32_e32 v15, v15
	v_bfe_i32 v250, v189, 24, 1
	v_and_b32_e32 v12, v13, v198
	v_fma_f32 v13, v92, s35, -v188
	v_exp_f32_e32 v13, v13
	v_bfe_i32 v251, v189, 25, 1
	v_fma_f32 v81, v95, s35, -v188
	v_and_b32_e32 v13, v13, v250
	v_exp_f32_e32 v81, v81
	v_bfe_i32 v252, v189, 26, 1
	v_and_b32_e32 v14, v15, v251
	v_fma_f32 v15, v94, s35, -v188
	v_exp_f32_e32 v15, v15
	v_bfe_i32 v198, v189, 27, 1
	v_cvt_pk_bf16_f32 v82, v0, v2
	v_cvt_pk_bf16_f32 v83, v3, v4
	v_cvt_pk_bf16_f32 v84, v5, v6
	v_cvt_pk_bf16_f32 v85, v7, v8
	s_nop 0
	v_and_b32_e32 v15, v15, v252
	v_cvt_pk_bf16_f32 v86, v9, v10
	v_cvt_pk_bf16_f32 v87, v11, v12
	v_cvt_pk_bf16_f32 v88, v13, v14
	s_add_i32 s6, s11, -2
	s_cmp_lt_i32 s6, s38
	v_and_b32_e32 v80, v81, v198
	v_cvt_pk_bf16_f32 v89, v15, v80
	s_nop 1
	v_mfma_f32_32x32x16_bf16 v[64:79], v[190:193], v[82:85], v[64:79]
	s_cselect_b64 s[8:9], -1, 0
	s_cmp_ge_i32 s6, s38
	v_mfma_f32_32x32x16_bf16 v[64:79], v[194:197], v[86:89], v[64:79]
	v_mfma_f32_32x32x16_bf16 v[48:63], v[226:229], v[82:85], v[48:63]
	v_mfma_f32_32x32x16_bf16 v[48:63], v[230:233], v[86:89], v[48:63]
	v_mfma_f32_32x32x16_bf16 v[32:47], v[234:237], v[82:85], v[32:47]
	v_mfma_f32_32x32x16_bf16 v[32:47], v[238:241], v[86:89], v[32:47]
	v_mfma_f32_32x32x16_bf16 v[16:31], v[242:245], v[82:85], v[16:31]
	v_mfma_f32_32x32x16_bf16 v[16:31], v[246:249], v[86:89], v[16:31]
	s_cbranch_scc1 .LBB0_824
	s_waitcnt vmcnt(3)
	ds_write_b128 v215, v[132:135] offset:16384
	s_waitcnt vmcnt(2)
	ds_write_b128 v216, v[140:143] offset:53248
	s_waitcnt vmcnt(1)
	ds_write_b128 v215, v[148:151] offset:24576
	s_waitcnt vmcnt(0)
	ds_write_b128 v216, v[156:159] offset:63488

; __device__ __forceinline__ void phase_attn(const Params& P, unsigned char* lds) {
;     ...
;             auto tile_body = [&](const int tile, const int buf) __attribute__((always_inline)) {
;                 f32x16 S;
; #pragma unroll
;                 for (int i = 0; i < 16; ++i) S[i] = 0.f;
;                 const unsigned char* kb = lds + ATT_K_OFF + buf * 16384 + lr * 512 + g * 256;
; #pragma unroll
;                 for (int kk = 0; kk < 8; ++kk) { const bf16x8 Kf = *(const bf16x8*)(kb + (((2 * kk + hh) ^ (lr & 15)) * 16)); S = __builtin_amdgcn_mfma_f32_32x32x16_bf16(Kf, Qf[kk], S, 0, 0, 0); }
;                 const unsigned bits2 = bm[lr * 65 + tile] >> (4 * hh);
;                 float mx = S[0];
; #pragma unroll
;                 for (int i = 1; i < 16; ++i) mx = __builtin_fmaxf(mx, S[i]);
;                 mx *= 0.12751743f;
;                 mx = __builtin_fmaxf(mx, __shfl_xor(mx, 32));
;                 if (__any(mx > m)) { const float mn = __builtin_fmaxf(m, mx), al = __builtin_amdgcn_exp2f(m - mn);
; #pragma unroll
;                     for (int d = 0; d < 4; ++d)
; #pragma unroll
;                         for (int i = 0; i < 16; ++i) o[d][i] *= al;
;                     l *= al; m = mn; }
.LBB0_827:
	ds_read_b128 v[2:5], v217 offset:16384
	ds_read_b128 v[6:9], v218 offset:16384
	ds_read_b128 v[226:229], v219 offset:16384
	ds_read_b128 v[230:233], v220 offset:16384
	ds_read_b128 v[234:237], v221 offset:16384
	ds_read_b128 v[238:241], v222 offset:16384
	ds_read_b128 v[242:245], v223 offset:16384
	ds_read_b128 v[246:249], v224 offset:16384
	s_waitcnt lgkmcnt(4)
	v_mfma_f32_32x32x16_bf16 v[80:95], v[2:5], v[96:99], 0
	v_mfma_f32_32x32x16_bf16 v[80:95], v[6:9], v[100:103], v[80:95]
	v_mfma_f32_32x32x16_bf16 v[80:95], v[226:229], v[104:107], v[80:95]
	v_mfma_f32_32x32x16_bf16 v[80:95], v[230:233], v[108:111], v[80:95]
	s_waitcnt lgkmcnt(0)
	v_mfma_f32_32x32x16_bf16 v[80:95], v[234:237], v[112:115], v[80:95]
	v_mfma_f32_32x32x16_bf16 v[80:95], v[238:241], v[116:119], v[80:95]
	v_mfma_f32_32x32x16_bf16 v[80:95], v[242:245], v[120:123], v[80:95]
	v_mfma_f32_32x32x16_bf16 v[80:95], v[246:249], v[124:127], v[80:95]
	ds_read_b128 v[190:193], v225 offset:53248
	ds_read_b128 v[194:197], v225 offset:53280
	ds_read_b128 v[226:229], v225 offset:55808
	ds_read_b128 v[230:233], v225 offset:55840
	ds_read_b128 v[234:237], v225 offset:58368
	ds_read_b128 v[238:241], v225 offset:58400
	ds_read_b128 v[242:245], v225 offset:60928
	ds_read_b128 v[246:249], v225 offset:60960
	s_nop 3
	v_max_f32_e32 v0, v81, v81
	v_max_f32_e32 v2, v80, v80
	v_max_f32_e32 v0, v2, v0
	v_max3_f32 v0, v0, v82, v83
	v_max3_f32 v0, v0, v84, v85
	v_max3_f32 v0, v0, v86, v87
	v_max3_f32 v0, v0, v88, v89
	v_max3_f32 v0, v0, v90, v91
	v_max3_f32 v0, v0, v92, v93
	v_max3_f32 v0, v0, v94, v95
	v_mul_f32_e32 v2, 0x3e0293ee, v0
	v_mov_b32_e32 v3, v2
	ds_read_b32 v0, v187
	s_nop 0
	v_permlane32_swap_b32_e32 v2, v3
	v_max_f32_e32 v2, v2, v3
	v_cmp_gt_f32_e32 vcc, v2, v188
	s_cbranch_vccz .LBB0_830
	v_max_f32_e32 v2, v2, v2
	v_max_f32_e32 v3, v188, v188
	v_max_f32_e32 v3, v3, v2
	v_sub_f32_e32 v2, v188, v3
	v_exp_f32_e32 v2, v2
	v_xor_b32_e32 v7, 0x80000000, v3
	v_mov_b32_e32 v188, v3
	v_pk_mul_f32 v[78:79], v[78:79], v[2:3] op_sel_hi:[1,0]
	v_pk_mul_f32 v[76:77], v[76:77], v[2:3] op_sel_hi:[1,0]
	v_pk_mul_f32 v[74:75], v[74:75], v[2:3] op_sel_hi:[1,0]
	v_pk_mul_f32 v[72:73], v[72:73], v[2:3] op_sel_hi:[1,0]
	v_pk_mul_f32 v[70:71], v[70:71], v[2:3] op_sel_hi:[1,0]
	v_pk_mul_f32 v[68:69], v[68:69], v[2:3] op_sel_hi:[1,0]
	v_pk_mul_f32 v[66:67], v[66:67], v[2:3] op_sel_hi:[1,0]
	v_pk_mul_f32 v[64:65], v[64:65], v[2:3] op_sel_hi:[1,0]
	v_pk_mul_f32 v[62:63], v[62:63], v[2:3] op_sel_hi:[1,0]
	v_pk_mul_f32 v[60:61], v[60:61], v[2:3] op_sel_hi:[1,0]
	v_pk_mul_f32 v[58:59], v[58:59], v[2:3] op_sel_hi:[1,0]
	v_pk_mul_f32 v[56:57], v[56:57], v[2:3] op_sel_hi:[1,0]
	v_pk_mul_f32 v[54:55], v[54:55], v[2:3] op_sel_hi:[1,0]
	v_pk_mul_f32 v[52:53], v[52:53], v[2:3] op_sel_hi:[1,0]
	v_pk_mul_f32 v[50:51], v[50:51], v[2:3] op_sel_hi:[1,0]
	v_pk_mul_f32 v[48:49], v[48:49], v[2:3] op_sel_hi:[1,0]
	v_pk_mul_f32 v[46:47], v[46:47], v[2:3] op_sel_hi:[1,0]
	v_pk_mul_f32 v[44:45], v[44:45], v[2:3] op_sel_hi:[1,0]
	v_pk_mul_f32 v[42:43], v[42:43], v[2:3] op_sel_hi:[1,0]
	v_pk_mul_f32 v[40:41], v[40:41], v[2:3] op_sel_hi:[1,0]
	v_pk_mul_f32 v[38:39], v[38:39], v[2:3] op_sel_hi:[1,0]
	v_pk_mul_f32 v[36:37], v[36:37], v[2:3] op_sel_hi:[1,0]
	v_pk_mul_f32 v[34:35], v[34:35], v[2:3] op_sel_hi:[1,0]
	v_pk_mul_f32 v[32:33], v[32:33], v[2:3] op_sel_hi:[1,0]
	v_pk_mul_f32 v[30:31], v[30:31], v[2:3] op_sel_hi:[1,0]
	v_pk_mul_f32 v[28:29], v[28:29], v[2:3] op_sel_hi:[1,0]
	v_pk_mul_f32 v[26:27], v[26:27], v[2:3] op_sel_hi:[1,0]
	v_pk_mul_f32 v[24:25], v[24:25], v[2:3] op_sel_hi:[1,0]
	v_pk_mul_f32 v[22:23], v[22:23], v[2:3] op_sel_hi:[1,0]
	v_pk_mul_f32 v[20:21], v[20:21], v[2:3] op_sel_hi:[1,0]
	v_pk_mul_f32 v[18:19], v[18:19], v[2:3] op_sel_hi:[1,0]
	v_pk_mul_f32 v[16:17], v[16:17], v[2:3] op_sel_hi:[1,0]
	v_mul_f32_e32 v183, v183, v2
	s_branch .LBB0_831

; __device__ __forceinline__ unsigned cvt_pk_bf16(float lo, float hi) { unsigned r; asm volatile("v_cvt_pk_bf16_f32 %0, %1, %2" : "=v"(r) : "v"(lo), "v"(hi)); return r; }
; __device__ __forceinline__ void phase_attn(const Params& P, unsigned char* lds) {
;     ...
;                 float pr[16];
; #pragma unroll
;                 for (int i = 0; i < 16; ++i) { const int mk = __builtin_amdgcn_sbfe((int)bits2, (i & 3) + 8 * (i >> 2), 1);
;                     const float e = __builtin_amdgcn_exp2f(__builtin_fmaf(S[i], 0.12751743f, -m));
;                     pr[i] = __int_as_float(__float_as_int(e) & mk); l += pr[i]; }
;                 bf16x8 Pf[2];
; #pragma unroll
;                 for (int s2 = 0; s2 < 2; ++s2) { u32x4 w; w.x = cvt_pk_bf16(pr[8 * s2 + 0], pr[8 * s2 + 1]); w.y = cvt_pk_bf16(pr[8 * s2 + 2], pr[8 * s2 + 3]);
;                     w.z = cvt_pk_bf16(pr[8 * s2 + 4], pr[8 * s2 + 5]); w.w = cvt_pk_bf16(pr[8 * s2 + 6], pr[8 * s2 + 7]); Pf[s2] = __builtin_bit_cast(bf16x8, w); }
;                 const unsigned char* vb = lds + ATT_V_OFF + buf * 20480 + (g * 128 + lr) * 80 + hh * 16;
; #pragma unroll
;                 for (int d = 0; d < 4; ++d)
; #pragma unroll
;                     for (int s2 = 0; s2 < 2; ++s2) { const bf16x8 Vf = *(const bf16x8*)(vb + d * 32 * 80 + s2 * 32); o[d] = __builtin_amdgcn_mfma_f32_32x32x16_bf16(Vf, Pf[s2], o[d], 0, 0, 0); }
;             };
;             ATT_LOAD(sKa, sVa, 0); ATT_STORE(sKa, sVa, 0);
;             if (1 < ntiles) ATT_LOAD(sKb, sVb, 1);
;             __syncthreads();
;             for (int tile = 0; tile < ntiles; tile += 2) {
;                 if (tile + 2 < ntiles) ATT_LOAD(sKa, sVa, tile + 2);
;                 tile_body(tile, 0);
;                 if (tile + 1 < ntiles) ATT_STORE(sKb, sVb, 1);
;                 __syncthreads();
;                 if (tile + 1 >= ntiles) break;
;                 if (tile + 3 < ntiles) ATT_LOAD(sKb, sVb, tile + 3);
;                 tile_body(tile + 1, 1);
;                 if (tile + 2 < ntiles) ATT_STORE(sKa, sVa, 0);
;                 __syncthreads();
.LBB0_831:
	s_waitcnt lgkmcnt(0)
	v_lshrrev_b32_e32 v189, v208, v0
	v_fmamk_f32 v0, v80, 0x3e0293ee, v7
	v_exp_f32_e32 v0, v0
	v_fmamk_f32 v3, v81, 0x3e0293ee, v7
	v_exp_f32_e32 v3, v3
	v_bfe_i32 v250, v189, 0, 1
	v_bfe_i32 v251, v189, 1, 1
	v_fmamk_f32 v5, v83, 0x3e0293ee, v7
	v_and_b32_e32 v0, v0, v250
	v_exp_f32_e32 v5, v5
	v_bfe_i32 v252, v189, 2, 1
	v_and_b32_e32 v2, v3, v251
	v_fmamk_f32 v3, v82, 0x3e0293ee, v7
	v_exp_f32_e32 v3, v3
	v_bfe_i32 v198, v189, 3, 1
	v_fmamk_f32 v8, v85, 0x3e0293ee, v7
	v_and_b32_e32 v3, v3, v252
	v_exp_f32_e32 v8, v8
	v_bfe_i32 v250, v189, 8, 1
	v_and_b32_e32 v4, v5, v198
	v_fmamk_f32 v5, v84, 0x3e0293ee, v7
	v_exp_f32_e32 v5, v5
	v_bfe_i32 v251, v189, 9, 1
	v_fmamk_f32 v10, v87, 0x3e0293ee, v7
	v_and_b32_e32 v5, v5, v250
	v_exp_f32_e32 v10, v10
	v_bfe_i32 v252, v189, 10, 1
	v_and_b32_e32 v6, v8, v251
	v_fmamk_f32 v8, v86, 0x3e0293ee, v7
	v_exp_f32_e32 v8, v8
	v_bfe_i32 v198, v189, 11, 1
	v_fmamk_f32 v12, v89, 0x3e0293ee, v7
	v_and_b32_e32 v8, v8, v252
	v_exp_f32_e32 v12, v12
	v_bfe_i32 v250, v189, 16, 1
	v_and_b32_e32 v9, v10, v198
	v_fmamk_f32 v10, v88, 0x3e0293ee, v7
	v_exp_f32_e32 v10, v10
	v_bfe_i32 v251, v189, 17, 1
	v_fmamk_f32 v14, v91, 0x3e0293ee, v7
	v_and_b32_e32 v10, v10, v250
	v_exp_f32_e32 v14, v14
	v_bfe_i32 v252, v189, 18, 1
	v_and_b32_e32 v11, v12, v251
	v_fmamk_f32 v12, v90, 0x3e0293ee, v7
	v_exp_f32_e32 v12, v12
	v_bfe_i32 v198, v189, 19, 1
	v_fmamk_f32 v80, v93, 0x3e0293ee, v7
	v_and_b32_e32 v12, v12, v252
	v_exp_f32_e32 v80, v80
	v_bfe_i32 v250, v189, 24, 1
	v_and_b32_e32 v13, v14, v198
	v_fmamk_f32 v14, v92, 0x3e0293ee, v7
	v_exp_f32_e32 v14, v14
	v_bfe_i32 v251, v189, 25, 1
	v_bfe_i32 v252, v189, 26, 1
	v_and_b32_e32 v14, v14, v250
	s_nop 1
	v_and_b32_e32 v15, v80, v251
	v_fmamk_f32 v80, v94, 0x3e0293ee, v7
	v_exp_f32_e32 v80, v80
	v_fmac_f32_e32 v7, 0x3e0293ee, v95
	v_exp_f32_e32 v82, v7
	s_nop 1
	v_and_b32_e32 v7, v80, v252
	v_bfe_i32 v198, v189, 27, 1
	s_nop 1
	v_and_b32_e32 v80, v82, v198
	v_cvt_pk_bf16_f32 v82, v0, v2
	v_cvt_pk_bf16_f32 v83, v3, v4
	v_cvt_pk_bf16_f32 v84, v5, v6
	v_cvt_pk_bf16_f32 v85, v8, v9
	v_cvt_pk_bf16_f32 v86, v10, v11
	v_cvt_pk_bf16_f32 v87, v12, v13
	v_cvt_pk_bf16_f32 v88, v14, v15
	v_cvt_pk_bf16_f32 v89, v7, v80
	s_nop 1
	v_mfma_f32_32x32x16_bf16 v[64:79], v[190:193], v[82:85], v[64:79]
	s_andn2_b64 vcc, exec, s[0:1]
	v_mfma_f32_32x32x16_bf16 v[64:79], v[194:197], v[86:89], v[64:79]
	v_mfma_f32_32x32x16_bf16 v[48:63], v[226:229], v[82:85], v[48:63]
	v_mfma_f32_32x32x16_bf16 v[48:63], v[230:233], v[86:89], v[48:63]
	v_mfma_f32_32x32x16_bf16 v[32:47], v[234:237], v[82:85], v[32:47]
	v_mfma_f32_32x32x16_bf16 v[32:47], v[238:241], v[86:89], v[32:47]
	v_mfma_f32_32x32x16_bf16 v[16:31], v[242:245], v[82:85], v[16:31]
	v_mfma_f32_32x32x16_bf16 v[16:31], v[246:249], v[86:89], v[16:31]
	s_cbranch_vccnz .LBB0_817
	s_waitcnt vmcnt(3)
	ds_write_b128 v215, v[128:131]
	s_waitcnt vmcnt(2)
	ds_write_b128 v216, v[136:139] offset:32768
	s_waitcnt vmcnt(1)
	ds_write_b128 v215, v[144:147] offset:8192
	s_waitcnt vmcnt(0)
	ds_write_b128 v216, v[152:155] offset:43008
	s_branch .LBB0_817

; __global__ void __launch_bounds__(512, 2) fwd_megakernel(Params P, int ph_lo, int ph_hi) {
	.amdhsa_kernel _Z14fwd_megakernel6Paramsii
		.amdhsa_group_segment_fixed_size 0
		.amdhsa_private_segment_fixed_size 0
		.amdhsa_kernarg_size 432
		.amdhsa_user_sgpr_count 2
		.amdhsa_user_sgpr_dispatch_ptr 0
		.amdhsa_user_sgpr_queue_ptr 0
		.amdhsa_user_sgpr_kernarg_segment_ptr 1
		.amdhsa_user_sgpr_dispatch_id 0
		.amdhsa_user_sgpr_kernarg_preload_length 0
		.amdhsa_user_sgpr_kernarg_preload_offset 0
		.amdhsa_user_sgpr_private_segment_size 0
		.amdhsa_uses_dynamic_stack 0
		.amdhsa_enable_private_segment 0
		.amdhsa_system_sgpr_workgroup_id_x 1
		.amdhsa_system_sgpr_workgroup_id_y 0
		.amdhsa_system_sgpr_workgroup_id_z 0
		.amdhsa_system_sgpr_workgroup_info 0
		.amdhsa_system_vgpr_workitem_id 2
		.amdhsa_next_free_vgpr 254
		.amdhsa_next_free_sgpr 102
		.amdhsa_accum_offset 256
		.amdhsa_reserve_vcc 1
		.amdhsa_float_round_mode_32 0
		.amdhsa_float_round_mode_16_64 0
		.amdhsa_float_denorm_mode_32 3
		.amdhsa_float_denorm_mode_16_64 3
		.amdhsa_dx10_clamp 1
		.amdhsa_ieee_mode 1
		.amdhsa_fp16_overflow 0
		.amdhsa_tg_split 0
		.amdhsa_exception_fp_ieee_invalid_op 0
		.amdhsa_exception_fp_denorm_src 0
		.amdhsa_exception_fp_ieee_div_zero 0
		.amdhsa_exception_fp_ieee_overflow 0
		.amdhsa_exception_fp_ieee_underflow 0
		.amdhsa_exception_fp_ieee_inexact 0
		.amdhsa_exception_int_div_zero 0
	.end_amdhsa_kernel

; __global__ void __launch_bounds__(512, 2) fwd_megakernel(Params P, int ph_lo, int ph_hi) {
amdhsa.kernels:
  - .agpr_count:     0
    .args:
      - .offset:         0
        .size:           168
        .value_kind:     by_value
      - .offset:         168
        .size:           4
        .value_kind:     by_value
      - .offset:         172
        .size:           4
        .value_kind:     by_value
      - .offset:         176
        .size:           4
        .value_kind:     hidden_block_count_x
      - .offset:         180
        .size:           4
        .value_kind:     hidden_block_count_y
      - .offset:         184
        .size:           4
        .value_kind:     hidden_block_count_z
      - .offset:         188
        .size:           2
        .value_kind:     hidden_group_size_x
      - .offset:         190
        .size:           2
        .value_kind:     hidden_group_size_y
      - .offset:         192
        .size:           2
        .value_kind:     hidden_group_size_z
      - .offset:         194
        .size:           2
        .value_kind:     hidden_remainder_x
      - .offset:         196
        .size:           2
        .value_kind:     hidden_remainder_y
      - .offset:         198
        .size:           2
        .value_kind:     hidden_remainder_z
      - .offset:         216
        .size:           8
        .value_kind:     hidden_global_offset_x
      - .offset:         224
        .size:           8
        .value_kind:     hidden_global_offset_y
      - .offset:         232
        .size:           8
        .value_kind:     hidden_global_offset_z
      - .offset:         240
        .size:           2
        .value_kind:     hidden_grid_dims
      - .offset:         264
        .size:           8
        .value_kind:     hidden_multigrid_sync_arg
      - .offset:         296
        .size:           4
        .value_kind:     hidden_dynamic_lds_size
    .group_segment_fixed_size: 0
    .kernarg_segment_align: 8
    .kernarg_segment_size: 432
    .language:       OpenCL C
    .language_version:
      - 2
      - 0
    .max_flat_workgroup_size: 512
    .name:           _Z14fwd_megakernel6Paramsii
    .private_segment_fixed_size: 0
    .sgpr_count:     108
    .sgpr_spill_count: 48
    .symbol:         _Z14fwd_megakernel6Paramsii.kd
    .uniform_work_group_size: 1
    .uses_dynamic_stack: false
    .vgpr_count:     254
    .vgpr_spill_count: 0
    .wavefront_size: 64
